# out-proj epilogue bf16/f32 stores also as buffer_store_dwordx4 with descriptor bases (on top of the in-proj buffer stores)
# baseline (speedup 1.0000x reference)
.LBB0_379:
	s_mov_b32 s80, s44
	s_and_b32 s81, s45, 0xffff
	s_mov_b32 s82, -1
	s_mov_b32 s83, 0x20000
	s_mov_b32 s84, s94
	s_and_b32 s85, s95, 0xffff
	s_mov_b32 s86, -1
	s_mov_b32 s87, 0x20000
	v_lshlrev_b32_e32 v0, 3, v172
	v_lshl_or_b32 v0, s5, 5, v0
	v_lshl_add_u32 v164, s0, 8, v140
	v_lshl_or_b32 v174, s16, 8, v0
	v_lshlrev_b32_e32 v0, 1, v174
	v_ashrrev_i32_e32 v165, 31, v164
	v_lshl_add_u64 v[166:167], s[44:45], 0, v[0:1]
	v_lshlrev_b64 v[130:131], 12, v[164:165]
	v_or_b32_e32 v162, 16, v164
	v_lshl_add_u64 v[130:131], v[166:167], 0, v[130:131]
	v_ashrrev_i32_e32 v163, 31, v162
	global_load_dwordx4 v[176:179], v[130:131], off
	global_load_dwordx4 v[154:157], v[130:131], off offset:256
	v_lshlrev_b64 v[130:131], 12, v[162:163]
	v_or_b32_e32 v160, 32, v164
	v_lshl_add_u64 v[130:131], v[166:167], 0, v[130:131]
	v_ashrrev_i32_e32 v161, 31, v160
	global_load_dwordx4 v[150:153], v[130:131], off
	global_load_dwordx4 v[146:149], v[130:131], off offset:256
	v_lshlrev_b64 v[130:131], 12, v[160:161]
	v_or_b32_e32 v158, 48, v164
	v_lshl_add_u64 v[130:131], v[166:167], 0, v[130:131]
	v_ashrrev_i32_e32 v159, 31, v158
	global_load_dwordx4 v[142:145], v[130:131], off
	global_load_dwordx4 v[138:141], v[130:131], off offset:256
	v_lshlrev_b64 v[130:131], 12, v[158:159]
	v_lshl_add_u64 v[130:131], v[166:167], 0, v[130:131]
	global_load_dwordx4 v[134:137], v[130:131], off
	s_nop 0
	global_load_dwordx4 v[130:133], v[130:131], off offset:256
	v_add_u32_e32 v218, 0x80, v164
	v_ashrrev_i32_e32 v219, 31, v218
	v_lshlrev_b64 v[220:221], 12, v[218:219]
	v_lshl_add_u64 v[220:221], v[166:167], 0, v[220:221]
	global_load_dwordx4 v[184:187], v[220:221], off
	global_load_dwordx4 v[188:191], v[220:221], off offset:256
	v_add_u32_e32 v218, 0x90, v164
	v_ashrrev_i32_e32 v219, 31, v218
	v_lshlrev_b64 v[220:221], 12, v[218:219]
	v_lshl_add_u64 v[220:221], v[166:167], 0, v[220:221]
	global_load_dwordx4 v[192:195], v[220:221], off
	global_load_dwordx4 v[196:199], v[220:221], off offset:256
	v_add_u32_e32 v218, 0xa0, v164
	v_ashrrev_i32_e32 v219, 31, v218
	v_lshlrev_b64 v[220:221], 12, v[218:219]
	v_lshl_add_u64 v[220:221], v[166:167], 0, v[220:221]
	global_load_dwordx4 v[200:203], v[220:221], off
	global_load_dwordx4 v[204:207], v[220:221], off offset:256
	v_add_u32_e32 v218, 0xb0, v164
	v_ashrrev_i32_e32 v219, 31, v218
	v_lshlrev_b64 v[220:221], 12, v[218:219]
	v_lshl_add_u64 v[220:221], v[166:167], 0, v[220:221]
	global_load_dwordx4 v[210:213], v[220:221], off
	global_load_dwordx4 v[214:217], v[220:221], off offset:256
	s_cmp_eq_u32 s78, 3
	s_cselect_b64 s[0:1], -1, 0
	s_cmp_lg_u32 s78, 3
	v_lshlrev_b64 v[170:171], 11, v[164:165]
	s_cselect_b64 s[6:7], -1, 0
	v_or_b32_e32 v170, v170, v174
	s_mov_b64 s[2:3], -1
	s_and_b64 vcc, exec, s[6:7]
	v_lshlrev_b32_e32 v168, 1, v170
	s_mov_b64 s[8:9], 0x100
	s_waitcnt vmcnt(8)
	v_lshlrev_b32_e32 v180, 16, v176
	v_and_b32_e32 v181, 0xffff0000, v176
	v_lshlrev_b32_e32 v176, 16, v177
	v_and_b32_e32 v177, 0xffff0000, v177
	v_lshlrev_b32_e32 v182, 16, v178
	v_and_b32_e32 v183, 0xffff0000, v178
	v_lshlrev_b32_e32 v178, 16, v179
	v_and_b32_e32 v179, 0xffff0000, v179
	v_pk_add_f32 v[128:129], v[128:129], v[176:177]
	v_pk_add_f32 v[126:127], v[126:127], v[180:181]
	v_pk_add_f32 v[124:125], v[124:125], v[178:179]
	v_pk_add_f32 v[122:123], v[122:123], v[182:183]
	s_cbranch_vccz .LBB0_381
	v_cvt_pk_bf16_f32 v176, v126, v127
	v_cvt_pk_bf16_f32 v177, v128, v129
	v_cvt_pk_bf16_f32 v178, v122, v123
	v_cvt_pk_bf16_f32 v179, v124, v125
	s_mov_b64 s[2:3], 0
	buffer_store_dwordx4 v[176:179], v168, s[80:83], 0 offen sc1
	s_nop 1
	v_pk_mul_f32 v[176:177], v[128:129], v[128:129]
	v_pk_mul_f32 v[178:179], v[126:127], v[126:127]
	s_nop 0
	v_pk_mov_b32 v[180:181], v[178:179], v[176:177] op_sel:[1,0]
	v_mov_b32_e32 v179, v177
	v_pk_add_f32 v[176:177], v[180:181], v[178:179]
	v_pk_mul_f32 v[178:179], v[124:125], v[124:125]
	v_pk_mul_f32 v[180:181], v[122:123], v[122:123]
	v_mov_b32_e32 v182, v178
	v_mov_b32_e32 v183, v180
	v_mov_b32_e32 v180, v179
	v_pk_add_f32 v[178:179], v[182:183], v[180:181]
	v_add_f32_e32 v0, v176, v177
	v_add_f32_e32 v0, v179, v0
	v_add_f32_e32 v175, v178, v0
.LBB0_381:
	s_andn2_b64 vcc, exec, s[2:3]
	v_lshlrev_b32_e32 v170, 2, v170
	s_cbranch_vccnz .LBB0_383
	v_mov_b32_e32 v175, 0
	buffer_store_dwordx4 v[126:129], v170, s[84:87], 0 offen
	buffer_store_dwordx4 v[122:125], v170, s[84:87], 0 offen offset:16
.LBB0_383:
	s_nop 1
	v_lshlrev_b32_e32 v122, 16, v154
	v_and_b32_e32 v123, 0xffff0000, v154
	v_lshlrev_b32_e32 v124, 16, v155
	v_and_b32_e32 v125, 0xffff0000, v155
	v_pk_add_f32 v[120:121], v[120:121], v[124:125]
	v_pk_add_f32 v[118:119], v[118:119], v[122:123]
	v_lshlrev_b32_e32 v122, 16, v156
	v_and_b32_e32 v123, 0xffff0000, v156
	v_lshlrev_b32_e32 v124, 16, v157
	v_and_b32_e32 v125, 0xffff0000, v157
	v_pk_add_f32 v[116:117], v[116:117], v[124:125]
	v_pk_add_f32 v[114:115], v[114:115], v[122:123]
	s_mov_b64 s[2:3], -1
	s_and_b64 vcc, exec, s[6:7]
	s_cbranch_vccz .LBB0_385
	v_cvt_pk_bf16_f32 v122, v118, v119
	v_cvt_pk_bf16_f32 v123, v120, v121
	v_cvt_pk_bf16_f32 v124, v114, v115
	v_cvt_pk_bf16_f32 v125, v116, v117
	v_add_u32_e32 v126, s8, v168
	buffer_store_dwordx4 v[122:125], v126, s[80:83], 0 offen sc1
	s_nop 1
	v_pk_mul_f32 v[122:123], v[120:121], v[120:121]
	v_pk_mul_f32 v[124:125], v[118:119], v[118:119]
	s_mov_b64 s[2:3], 0
	v_pk_mov_b32 v[126:127], v[124:125], v[122:123] op_sel:[1,0]
	v_mov_b32_e32 v125, v123
	v_pk_add_f32 v[122:123], v[126:127], v[124:125]
	v_pk_mul_f32 v[124:125], v[116:117], v[116:117]
	v_pk_mul_f32 v[126:127], v[114:115], v[114:115]
	v_mov_b32_e32 v128, v124
	v_mov_b32_e32 v129, v126
	v_mov_b32_e32 v126, v125
	v_pk_add_f32 v[124:125], v[128:129], v[126:127]
	v_add_f32_e32 v0, v122, v123
	v_add_f32_e32 v0, v125, v0
	v_add_f32_e32 v0, v124, v0
	v_add_f32_e32 v0, v0, v175
.LBB0_385:
	s_andn2_b64 vcc, exec, s[2:3]
	s_cbranch_vccnz .LBB0_387
	v_mov_b32_e32 v0, v175
	buffer_store_dwordx4 v[118:121], v170, s[84:87], 0 offen offset:512
	buffer_store_dwordx4 v[114:117], v170, s[84:87], 0 offen offset:528
.LBB0_387:
	s_nop 1
	v_lshlrev_b64 v[116:117], 11, v[162:163]
	v_lshlrev_b32_e32 v114, 16, v150
	v_and_b32_e32 v115, 0xffff0000, v150
	v_lshlrev_b32_e32 v118, 16, v151
	v_and_b32_e32 v119, 0xffff0000, v151
	v_or_b32_e32 v116, v116, v174
	v_pk_add_f32 v[112:113], v[112:113], v[118:119]
	v_pk_add_f32 v[110:111], v[110:111], v[114:115]
	v_lshlrev_b32_e32 v114, 16, v152
	v_and_b32_e32 v115, 0xffff0000, v152
	v_lshlrev_b32_e32 v118, 16, v153
	v_and_b32_e32 v119, 0xffff0000, v153
	v_pk_add_f32 v[108:109], v[108:109], v[118:119]
	v_pk_add_f32 v[106:107], v[106:107], v[114:115]
	s_mov_b64 s[2:3], -1
	s_and_b64 vcc, exec, s[6:7]
	v_lshlrev_b32_e32 v114, 1, v116
	s_cbranch_vccz .LBB0_389
	v_cvt_pk_bf16_f32 v118, v110, v111
	v_cvt_pk_bf16_f32 v119, v112, v113
	v_cvt_pk_bf16_f32 v120, v106, v107
	v_cvt_pk_bf16_f32 v121, v108, v109
	s_mov_b64 s[2:3], 0
	buffer_store_dwordx4 v[118:121], v114, s[80:83], 0 offen sc1
	s_nop 1
	v_pk_mul_f32 v[118:119], v[112:113], v[112:113]
	v_pk_mul_f32 v[120:121], v[110:111], v[110:111]
	s_nop 0
	v_pk_mov_b32 v[122:123], v[120:121], v[118:119] op_sel:[1,0]
	v_mov_b32_e32 v121, v119
	v_pk_add_f32 v[118:119], v[122:123], v[120:121]
	v_pk_mul_f32 v[120:121], v[108:109], v[108:109]
	v_pk_mul_f32 v[122:123], v[106:107], v[106:107]
	v_mov_b32_e32 v124, v120
	v_mov_b32_e32 v125, v122
	v_mov_b32_e32 v122, v121
	v_pk_add_f32 v[120:121], v[124:125], v[122:123]
	v_add_f32_e32 v118, v118, v119
	v_add_f32_e32 v118, v121, v118
	v_add_f32_e32 v118, v120, v118
.LBB0_389:
	s_andn2_b64 vcc, exec, s[2:3]
	v_lshlrev_b32_e32 v116, 2, v116
	s_cbranch_vccnz .LBB0_391
	v_mov_b32_e32 v118, 0
	buffer_store_dwordx4 v[110:113], v116, s[84:87], 0 offen
	buffer_store_dwordx4 v[106:109], v116, s[84:87], 0 offen offset:16
.LBB0_391:
	s_nop 1
	v_lshlrev_b32_e32 v106, 16, v146
	v_and_b32_e32 v107, 0xffff0000, v146
	v_lshlrev_b32_e32 v108, 16, v147
	v_and_b32_e32 v109, 0xffff0000, v147
	v_pk_add_f32 v[104:105], v[104:105], v[108:109]
	v_pk_add_f32 v[102:103], v[102:103], v[106:107]
	v_lshlrev_b32_e32 v106, 16, v148
	v_and_b32_e32 v107, 0xffff0000, v148
	v_lshlrev_b32_e32 v108, 16, v149
	v_and_b32_e32 v109, 0xffff0000, v149
	v_pk_add_f32 v[100:101], v[100:101], v[108:109]
	v_pk_add_f32 v[98:99], v[98:99], v[106:107]
	s_mov_b64 s[2:3], -1
	s_and_b64 vcc, exec, s[6:7]
	s_cbranch_vccz .LBB0_393
	v_cvt_pk_bf16_f32 v106, v102, v103
	v_cvt_pk_bf16_f32 v107, v104, v105
	v_cvt_pk_bf16_f32 v108, v98, v99
	v_cvt_pk_bf16_f32 v109, v100, v101
	v_add_u32_e32 v110, s8, v114
	buffer_store_dwordx4 v[106:109], v110, s[80:83], 0 offen sc1
	s_nop 1
	v_pk_mul_f32 v[106:107], v[104:105], v[104:105]
	v_pk_mul_f32 v[108:109], v[102:103], v[102:103]
	s_mov_b64 s[2:3], 0
	v_pk_mov_b32 v[110:111], v[108:109], v[106:107] op_sel:[1,0]
	v_mov_b32_e32 v109, v107
	v_pk_add_f32 v[106:107], v[110:111], v[108:109]
	v_pk_mul_f32 v[108:109], v[100:101], v[100:101]
	v_pk_mul_f32 v[110:111], v[98:99], v[98:99]
	v_mov_b32_e32 v112, v108
	v_mov_b32_e32 v113, v110
	v_mov_b32_e32 v110, v109
	v_pk_add_f32 v[108:109], v[112:113], v[110:111]
	v_add_f32_e32 v106, v106, v107
	v_add_f32_e32 v106, v109, v106
	v_add_f32_e32 v106, v108, v106
	v_add_f32_e32 v106, v106, v118
.LBB0_393:
	s_andn2_b64 vcc, exec, s[2:3]
	s_cbranch_vccnz .LBB0_395
	v_mov_b32_e32 v106, v118
	buffer_store_dwordx4 v[102:105], v116, s[84:87], 0 offen offset:512
	buffer_store_dwordx4 v[98:101], v116, s[84:87], 0 offen offset:528
.LBB0_395:
	s_nop 1
	v_lshlrev_b64 v[100:101], 11, v[160:161]
	v_lshlrev_b32_e32 v98, 16, v142
	v_and_b32_e32 v99, 0xffff0000, v142
	v_lshlrev_b32_e32 v102, 16, v143
	v_and_b32_e32 v103, 0xffff0000, v143
	v_or_b32_e32 v100, v100, v174
	v_pk_add_f32 v[96:97], v[96:97], v[102:103]
	v_pk_add_f32 v[94:95], v[94:95], v[98:99]
	v_lshlrev_b32_e32 v98, 16, v144
	v_and_b32_e32 v99, 0xffff0000, v144
	v_lshlrev_b32_e32 v102, 16, v145
	v_and_b32_e32 v103, 0xffff0000, v145
	v_pk_add_f32 v[92:93], v[92:93], v[102:103]
	v_pk_add_f32 v[90:91], v[90:91], v[98:99]
	s_mov_b64 s[2:3], -1
	s_and_b64 vcc, exec, s[6:7]
	v_lshlrev_b32_e32 v98, 1, v100
	s_cbranch_vccz .LBB0_397
	v_cvt_pk_bf16_f32 v102, v94, v95
	v_cvt_pk_bf16_f32 v103, v96, v97
	v_cvt_pk_bf16_f32 v104, v90, v91
	v_cvt_pk_bf16_f32 v105, v92, v93
	s_mov_b64 s[2:3], 0
	buffer_store_dwordx4 v[102:105], v98, s[80:83], 0 offen sc1
	s_nop 1
	v_pk_mul_f32 v[102:103], v[96:97], v[96:97]
	v_pk_mul_f32 v[104:105], v[94:95], v[94:95]
	s_nop 0
	v_pk_mov_b32 v[108:109], v[104:105], v[102:103] op_sel:[1,0]
	v_mov_b32_e32 v105, v103
	v_pk_add_f32 v[102:103], v[108:109], v[104:105]
	v_pk_mul_f32 v[104:105], v[92:93], v[92:93]
	v_pk_mul_f32 v[108:109], v[90:91], v[90:91]
	v_mov_b32_e32 v110, v104
	v_mov_b32_e32 v111, v108
	v_mov_b32_e32 v108, v105
	v_pk_add_f32 v[104:105], v[110:111], v[108:109]
	v_add_f32_e32 v102, v102, v103
	v_add_f32_e32 v102, v105, v102
	v_add_f32_e32 v102, v104, v102
.LBB0_397:
	s_andn2_b64 vcc, exec, s[2:3]
	v_lshlrev_b32_e32 v100, 2, v100
	s_cbranch_vccnz .LBB0_399
	v_mov_b32_e32 v102, 0
	buffer_store_dwordx4 v[94:97], v100, s[84:87], 0 offen
	buffer_store_dwordx4 v[90:93], v100, s[84:87], 0 offen offset:16
.LBB0_399:
	s_nop 1
	v_lshlrev_b32_e32 v90, 16, v138
	v_and_b32_e32 v91, 0xffff0000, v138
	v_lshlrev_b32_e32 v92, 16, v139
	v_and_b32_e32 v93, 0xffff0000, v139
	v_pk_add_f32 v[88:89], v[88:89], v[92:93]
	v_pk_add_f32 v[86:87], v[86:87], v[90:91]
	v_lshlrev_b32_e32 v90, 16, v140
	v_and_b32_e32 v91, 0xffff0000, v140
	v_lshlrev_b32_e32 v92, 16, v141
	v_and_b32_e32 v93, 0xffff0000, v141
	v_pk_add_f32 v[84:85], v[84:85], v[92:93]
	v_pk_add_f32 v[82:83], v[82:83], v[90:91]
	s_mov_b64 s[2:3], -1
	s_and_b64 vcc, exec, s[6:7]
	s_cbranch_vccz .LBB0_401
	v_cvt_pk_bf16_f32 v90, v86, v87
	v_cvt_pk_bf16_f32 v91, v88, v89
	v_cvt_pk_bf16_f32 v92, v82, v83
	v_cvt_pk_bf16_f32 v93, v84, v85
	v_add_u32_e32 v94, s8, v98
	buffer_store_dwordx4 v[90:93], v94, s[80:83], 0 offen sc1
	s_nop 1
	v_pk_mul_f32 v[90:91], v[88:89], v[88:89]
	v_pk_mul_f32 v[92:93], v[86:87], v[86:87]
	s_mov_b64 s[2:3], 0
	v_pk_mov_b32 v[94:95], v[92:93], v[90:91] op_sel:[1,0]
	v_mov_b32_e32 v93, v91
	v_pk_add_f32 v[90:91], v[94:95], v[92:93]
	v_pk_mul_f32 v[92:93], v[84:85], v[84:85]
	v_pk_mul_f32 v[94:95], v[82:83], v[82:83]
	v_mov_b32_e32 v96, v92
	v_mov_b32_e32 v97, v94
	v_mov_b32_e32 v94, v93
	v_pk_add_f32 v[92:93], v[96:97], v[94:95]
	v_add_f32_e32 v90, v90, v91
	v_add_f32_e32 v90, v93, v90
	v_add_f32_e32 v90, v92, v90
	v_add_f32_e32 v107, v90, v102
.LBB0_401:
	s_andn2_b64 vcc, exec, s[2:3]
	s_cbranch_vccnz .LBB0_403
	v_mov_b32_e32 v107, v102
	buffer_store_dwordx4 v[86:89], v100, s[84:87], 0 offen offset:512
	buffer_store_dwordx4 v[82:85], v100, s[84:87], 0 offen offset:528
.LBB0_403:
	s_nop 1
	v_lshlrev_b64 v[84:85], 11, v[158:159]
	v_lshlrev_b32_e32 v82, 16, v134
	v_and_b32_e32 v83, 0xffff0000, v134
	v_lshlrev_b32_e32 v86, 16, v135
	v_and_b32_e32 v87, 0xffff0000, v135
	v_or_b32_e32 v84, v84, v174
	v_pk_add_f32 v[80:81], v[80:81], v[86:87]
	v_pk_add_f32 v[78:79], v[78:79], v[82:83]
	v_lshlrev_b32_e32 v82, 16, v136
	v_and_b32_e32 v83, 0xffff0000, v136
	v_lshlrev_b32_e32 v86, 16, v137
	v_and_b32_e32 v87, 0xffff0000, v137
	v_pk_add_f32 v[76:77], v[76:77], v[86:87]
	v_pk_add_f32 v[74:75], v[74:75], v[82:83]
	s_mov_b64 s[2:3], -1
	s_and_b64 vcc, exec, s[6:7]
	v_lshlrev_b32_e32 v82, 1, v84
	s_cbranch_vccz .LBB0_405
	v_cvt_pk_bf16_f32 v86, v78, v79
	v_cvt_pk_bf16_f32 v87, v80, v81
	v_cvt_pk_bf16_f32 v88, v74, v75
	v_cvt_pk_bf16_f32 v89, v76, v77
	s_mov_b64 s[2:3], 0
	buffer_store_dwordx4 v[86:89], v82, s[80:83], 0 offen sc1
	s_nop 1
	v_pk_mul_f32 v[86:87], v[80:81], v[80:81]
	v_pk_mul_f32 v[88:89], v[78:79], v[78:79]
	s_nop 0
	v_pk_mov_b32 v[90:91], v[88:89], v[86:87] op_sel:[1,0]
	v_mov_b32_e32 v89, v87
	v_pk_add_f32 v[86:87], v[90:91], v[88:89]
	v_pk_mul_f32 v[88:89], v[76:77], v[76:77]
	v_pk_mul_f32 v[90:91], v[74:75], v[74:75]
	v_mov_b32_e32 v92, v88
	v_mov_b32_e32 v93, v90
	v_mov_b32_e32 v90, v89
	v_pk_add_f32 v[88:89], v[92:93], v[90:91]
	v_add_f32_e32 v86, v86, v87
	v_add_f32_e32 v86, v89, v86
	v_add_f32_e32 v86, v88, v86
.LBB0_405:
	s_andn2_b64 vcc, exec, s[2:3]
	v_lshlrev_b32_e32 v84, 2, v84
	s_cbranch_vccnz .LBB0_407
	v_mov_b32_e32 v86, 0
	buffer_store_dwordx4 v[78:81], v84, s[84:87], 0 offen
	buffer_store_dwordx4 v[74:77], v84, s[84:87], 0 offen offset:16
.LBB0_407:
	s_nop 1
	v_lshlrev_b32_e32 v74, 16, v130
	v_and_b32_e32 v75, 0xffff0000, v130
	v_lshlrev_b32_e32 v76, 16, v131
	v_and_b32_e32 v77, 0xffff0000, v131
	v_pk_add_f32 v[72:73], v[72:73], v[76:77]
	v_pk_add_f32 v[70:71], v[70:71], v[74:75]
	v_lshlrev_b32_e32 v74, 16, v132
	v_and_b32_e32 v75, 0xffff0000, v132
	v_lshlrev_b32_e32 v76, 16, v133
	v_and_b32_e32 v77, 0xffff0000, v133
	v_pk_add_f32 v[68:69], v[68:69], v[76:77]
	v_pk_add_f32 v[66:67], v[66:67], v[74:75]
	s_mov_b64 s[2:3], -1
	s_and_b64 vcc, exec, s[6:7]
	s_cbranch_vccz .LBB0_409
	v_cvt_pk_bf16_f32 v74, v70, v71
	v_cvt_pk_bf16_f32 v75, v72, v73
	v_cvt_pk_bf16_f32 v76, v66, v67
	v_cvt_pk_bf16_f32 v77, v68, v69
	v_add_u32_e32 v78, s8, v82
	buffer_store_dwordx4 v[74:77], v78, s[80:83], 0 offen sc1
	s_nop 1
	v_pk_mul_f32 v[74:75], v[72:73], v[72:73]
	v_pk_mul_f32 v[76:77], v[70:71], v[70:71]
	s_mov_b64 s[2:3], 0
	v_pk_mov_b32 v[78:79], v[76:77], v[74:75] op_sel:[1,0]
	v_mov_b32_e32 v77, v75
	v_pk_add_f32 v[74:75], v[78:79], v[76:77]
	v_pk_mul_f32 v[76:77], v[68:69], v[68:69]
	v_pk_mul_f32 v[78:79], v[66:67], v[66:67]
	v_mov_b32_e32 v80, v76
	v_mov_b32_e32 v81, v78
	v_mov_b32_e32 v78, v77
	v_pk_add_f32 v[76:77], v[80:81], v[78:79]
	v_add_f32_e32 v74, v74, v75
	v_add_f32_e32 v74, v77, v74
	v_add_f32_e32 v74, v76, v74
	v_add_f32_e32 v108, v74, v86
.LBB0_409:
	s_andn2_b64 vcc, exec, s[2:3]
	s_cbranch_vccnz .LBB0_411
	v_mov_b32_e32 v108, v86
	buffer_store_dwordx4 v[70:73], v84, s[84:87], 0 offen offset:512
	buffer_store_dwordx4 v[66:69], v84, s[84:87], 0 offen offset:528
.LBB0_411:
	v_add_u32_e32 v100, 0x80, v164
	v_ashrrev_i32_e32 v101, 31, v100
	v_lshlrev_b64 v[66:67], 12, v[100:101]
	v_add_u32_e32 v98, 0x90, v164
	v_lshl_add_u64 v[66:67], v[166:167], 0, v[66:67]
	v_ashrrev_i32_e32 v99, 31, v98
	s_waitcnt vmcnt(8)
	v_mov_b32_e32 v110, v184
	v_mov_b32_e32 v111, v185
	v_mov_b32_e32 v112, v186
	v_mov_b32_e32 v113, v187
	v_mov_b32_e32 v90, v188
	v_mov_b32_e32 v91, v189
	v_mov_b32_e32 v92, v190
	v_mov_b32_e32 v93, v191
	v_lshlrev_b64 v[66:67], 12, v[98:99]
	v_add_u32_e32 v96, 0xa0, v164
	v_lshl_add_u64 v[66:67], v[166:167], 0, v[66:67]
	v_ashrrev_i32_e32 v97, 31, v96
	v_mov_b32_e32 v86, v192
	v_mov_b32_e32 v87, v193
	v_mov_b32_e32 v88, v194
	v_mov_b32_e32 v89, v195
	v_mov_b32_e32 v82, v196
	v_mov_b32_e32 v83, v197
	v_mov_b32_e32 v84, v198
	v_mov_b32_e32 v85, v199
	v_lshlrev_b64 v[66:67], 12, v[96:97]
	v_add_u32_e32 v94, 0xb0, v164
	v_lshl_add_u64 v[66:67], v[166:167], 0, v[66:67]
	v_ashrrev_i32_e32 v95, 31, v94
	v_mov_b32_e32 v78, v200
	v_mov_b32_e32 v79, v201
	v_mov_b32_e32 v80, v202
	v_mov_b32_e32 v81, v203
	v_mov_b32_e32 v74, v204
	v_mov_b32_e32 v75, v205
	v_mov_b32_e32 v76, v206
	v_mov_b32_e32 v77, v207
	v_lshlrev_b64 v[66:67], 12, v[94:95]
	v_lshl_add_u64 v[66:67], v[166:167], 0, v[66:67]
	v_mov_b32_e32 v70, v210
	v_mov_b32_e32 v71, v211
	v_mov_b32_e32 v72, v212
	v_mov_b32_e32 v73, v213
	s_nop 0
	v_mov_b32_e32 v66, v214
	v_mov_b32_e32 v67, v215
	v_mov_b32_e32 v68, v216
	v_mov_b32_e32 v69, v217
	v_lshlrev_b64 v[104:105], 11, v[100:101]
	v_or_b32_e32 v104, v104, v174
	s_mov_b64 s[2:3], -1
	s_and_b64 vcc, exec, s[6:7]
	v_lshlrev_b32_e32 v102, 1, v104
	v_lshlrev_b32_e32 v114, 16, v110
	v_and_b32_e32 v115, 0xffff0000, v110
	v_lshlrev_b32_e32 v110, 16, v111
	v_and_b32_e32 v111, 0xffff0000, v111
	v_lshlrev_b32_e32 v116, 16, v112
	v_and_b32_e32 v117, 0xffff0000, v112
	v_lshlrev_b32_e32 v112, 16, v113
	v_and_b32_e32 v113, 0xffff0000, v113
	v_pk_add_f32 v[64:65], v[64:65], v[110:111]
	v_pk_add_f32 v[62:63], v[62:63], v[114:115]
	v_pk_add_f32 v[60:61], v[60:61], v[112:113]
	v_pk_add_f32 v[58:59], v[58:59], v[116:117]
	s_cbranch_vccz .LBB0_413
	v_cvt_pk_bf16_f32 v110, v62, v63
	v_cvt_pk_bf16_f32 v111, v64, v65
	v_cvt_pk_bf16_f32 v112, v58, v59
	v_cvt_pk_bf16_f32 v113, v60, v61
	s_mov_b64 s[2:3], 0
	buffer_store_dwordx4 v[110:113], v102, s[80:83], 0 offen sc1
	s_nop 1
	v_pk_mul_f32 v[110:111], v[64:65], v[64:65]
	v_pk_mul_f32 v[112:113], v[62:63], v[62:63]
	s_nop 0
	v_pk_mov_b32 v[114:115], v[112:113], v[110:111] op_sel:[1,0]
	v_mov_b32_e32 v113, v111
	v_pk_add_f32 v[110:111], v[114:115], v[112:113]
	v_pk_mul_f32 v[112:113], v[60:61], v[60:61]
	v_pk_mul_f32 v[114:115], v[58:59], v[58:59]
	v_mov_b32_e32 v116, v112
	v_mov_b32_e32 v117, v114
	v_mov_b32_e32 v114, v113
	v_pk_add_f32 v[112:113], v[116:117], v[114:115]
	v_add_f32_e32 v109, v110, v111
	v_add_f32_e32 v109, v113, v109
	v_add_f32_e32 v109, v112, v109
.LBB0_413:
	s_andn2_b64 vcc, exec, s[2:3]
	v_lshlrev_b32_e32 v104, 2, v104
	s_cbranch_vccnz .LBB0_415
	v_mov_b32_e32 v109, 0
	buffer_store_dwordx4 v[62:65], v104, s[84:87], 0 offen
	buffer_store_dwordx4 v[58:61], v104, s[84:87], 0 offen offset:16
.LBB0_415:
	s_nop 0
	v_lshlrev_b32_e32 v58, 16, v90
	v_and_b32_e32 v59, 0xffff0000, v90
	v_lshlrev_b32_e32 v60, 16, v91
	v_and_b32_e32 v61, 0xffff0000, v91
	v_pk_add_f32 v[56:57], v[56:57], v[60:61]
	v_pk_add_f32 v[54:55], v[54:55], v[58:59]
	v_lshlrev_b32_e32 v58, 16, v92
	v_and_b32_e32 v59, 0xffff0000, v92
	v_lshlrev_b32_e32 v60, 16, v93
	v_and_b32_e32 v61, 0xffff0000, v93
	v_pk_add_f32 v[52:53], v[52:53], v[60:61]
	v_pk_add_f32 v[50:51], v[50:51], v[58:59]
	s_mov_b64 s[2:3], -1
	s_and_b64 vcc, exec, s[6:7]
	s_cbranch_vccz .LBB0_417
	v_cvt_pk_bf16_f32 v58, v54, v55
	v_cvt_pk_bf16_f32 v59, v56, v57
	v_cvt_pk_bf16_f32 v60, v50, v51
	v_cvt_pk_bf16_f32 v61, v52, v53
	v_add_u32_e32 v62, s8, v102
	buffer_store_dwordx4 v[58:61], v62, s[80:83], 0 offen sc1
	s_nop 1
	v_pk_mul_f32 v[58:59], v[56:57], v[56:57]
	v_pk_mul_f32 v[60:61], v[54:55], v[54:55]
	s_mov_b64 s[2:3], 0
	v_pk_mov_b32 v[62:63], v[60:61], v[58:59] op_sel:[1,0]
	v_mov_b32_e32 v61, v59
	v_pk_add_f32 v[58:59], v[62:63], v[60:61]
	v_pk_mul_f32 v[60:61], v[52:53], v[52:53]
	v_pk_mul_f32 v[62:63], v[50:51], v[50:51]
	v_mov_b32_e32 v64, v60
	v_mov_b32_e32 v65, v62
	v_mov_b32_e32 v62, v61
	v_pk_add_f32 v[60:61], v[64:65], v[62:63]
	v_add_f32_e32 v58, v58, v59
	v_add_f32_e32 v58, v61, v58
	v_add_f32_e32 v58, v60, v58
	v_add_f32_e32 v58, v58, v109
.LBB0_417:
	s_andn2_b64 vcc, exec, s[2:3]
	s_cbranch_vccnz .LBB0_419
	v_mov_b32_e32 v58, v109
	buffer_store_dwordx4 v[54:57], v104, s[84:87], 0 offen offset:512
	buffer_store_dwordx4 v[50:53], v104, s[84:87], 0 offen offset:528
.LBB0_419:
	s_nop 1
	v_lshlrev_b64 v[52:53], 11, v[98:99]
	v_lshlrev_b32_e32 v50, 16, v86
	v_and_b32_e32 v51, 0xffff0000, v86
	v_lshlrev_b32_e32 v54, 16, v87
	v_and_b32_e32 v55, 0xffff0000, v87
	v_or_b32_e32 v52, v52, v174
	v_pk_add_f32 v[48:49], v[48:49], v[54:55]
	v_pk_add_f32 v[46:47], v[46:47], v[50:51]
	v_lshlrev_b32_e32 v50, 16, v88
	v_and_b32_e32 v51, 0xffff0000, v88
	v_lshlrev_b32_e32 v54, 16, v89
	v_and_b32_e32 v55, 0xffff0000, v89
	v_pk_add_f32 v[44:45], v[44:45], v[54:55]
	v_pk_add_f32 v[42:43], v[42:43], v[50:51]
	s_mov_b64 s[2:3], -1
	s_and_b64 vcc, exec, s[6:7]
	v_lshlrev_b32_e32 v50, 1, v52
	s_cbranch_vccz .LBB0_421
	v_cvt_pk_bf16_f32 v54, v46, v47
	v_cvt_pk_bf16_f32 v55, v48, v49
	v_cvt_pk_bf16_f32 v56, v42, v43
	v_cvt_pk_bf16_f32 v57, v44, v45
	s_mov_b64 s[2:3], 0
	buffer_store_dwordx4 v[54:57], v50, s[80:83], 0 offen sc1
	s_nop 1
	v_pk_mul_f32 v[54:55], v[48:49], v[48:49]
	v_pk_mul_f32 v[56:57], v[46:47], v[46:47]
	s_nop 0
	v_pk_mov_b32 v[60:61], v[56:57], v[54:55] op_sel:[1,0]
	v_mov_b32_e32 v57, v55
	v_pk_add_f32 v[54:55], v[60:61], v[56:57]
	v_pk_mul_f32 v[56:57], v[44:45], v[44:45]
	v_pk_mul_f32 v[60:61], v[42:43], v[42:43]
	v_mov_b32_e32 v62, v56
	v_mov_b32_e32 v63, v60
	v_mov_b32_e32 v60, v57
	v_pk_add_f32 v[56:57], v[62:63], v[60:61]
	v_add_f32_e32 v54, v54, v55
	v_add_f32_e32 v54, v57, v54
	v_add_f32_e32 v54, v56, v54
.LBB0_421:
	s_andn2_b64 vcc, exec, s[2:3]
	v_lshlrev_b32_e32 v52, 2, v52
	s_cbranch_vccnz .LBB0_423
	v_mov_b32_e32 v54, 0
	buffer_store_dwordx4 v[46:49], v52, s[84:87], 0 offen
	buffer_store_dwordx4 v[42:45], v52, s[84:87], 0 offen offset:16
.LBB0_423:
	s_nop 0
	v_lshlrev_b32_e32 v42, 16, v82
	v_and_b32_e32 v43, 0xffff0000, v82
	v_lshlrev_b32_e32 v44, 16, v83
	v_and_b32_e32 v45, 0xffff0000, v83
	v_pk_add_f32 v[40:41], v[40:41], v[44:45]
	v_pk_add_f32 v[38:39], v[38:39], v[42:43]
	v_lshlrev_b32_e32 v42, 16, v84
	v_and_b32_e32 v43, 0xffff0000, v84
	v_lshlrev_b32_e32 v44, 16, v85
	v_and_b32_e32 v45, 0xffff0000, v85
	v_pk_add_f32 v[36:37], v[36:37], v[44:45]
	v_pk_add_f32 v[34:35], v[34:35], v[42:43]
	s_mov_b64 s[2:3], -1
	s_and_b64 vcc, exec, s[6:7]
	s_cbranch_vccz .LBB0_425
	v_cvt_pk_bf16_f32 v42, v38, v39
	v_cvt_pk_bf16_f32 v43, v40, v41
	v_cvt_pk_bf16_f32 v44, v34, v35
	v_cvt_pk_bf16_f32 v45, v36, v37
	v_add_u32_e32 v46, s8, v50
	buffer_store_dwordx4 v[42:45], v46, s[80:83], 0 offen sc1
	s_nop 1
	v_pk_mul_f32 v[42:43], v[40:41], v[40:41]
	v_pk_mul_f32 v[44:45], v[38:39], v[38:39]
	s_mov_b64 s[2:3], 0
	v_pk_mov_b32 v[46:47], v[44:45], v[42:43] op_sel:[1,0]
	v_mov_b32_e32 v45, v43
	v_pk_add_f32 v[42:43], v[46:47], v[44:45]
	v_pk_mul_f32 v[44:45], v[36:37], v[36:37]
	v_pk_mul_f32 v[46:47], v[34:35], v[34:35]
	v_mov_b32_e32 v48, v44
	v_mov_b32_e32 v49, v46
	v_mov_b32_e32 v46, v45
	v_pk_add_f32 v[44:45], v[48:49], v[46:47]
	v_add_f32_e32 v42, v42, v43
	v_add_f32_e32 v42, v45, v42
	v_add_f32_e32 v42, v44, v42
	v_add_f32_e32 v42, v42, v54
.LBB0_425:
	s_andn2_b64 vcc, exec, s[2:3]
	s_cbranch_vccnz .LBB0_427
	v_mov_b32_e32 v42, v54
	buffer_store_dwordx4 v[38:41], v52, s[84:87], 0 offen offset:512
	buffer_store_dwordx4 v[34:37], v52, s[84:87], 0 offen offset:528
.LBB0_427:
	s_nop 1
	v_lshlrev_b64 v[36:37], 11, v[96:97]
	v_lshlrev_b32_e32 v34, 16, v78
	v_and_b32_e32 v35, 0xffff0000, v78
	v_lshlrev_b32_e32 v38, 16, v79
	v_and_b32_e32 v39, 0xffff0000, v79
	v_or_b32_e32 v36, v36, v174
	v_pk_add_f32 v[32:33], v[32:33], v[38:39]
	v_pk_add_f32 v[30:31], v[30:31], v[34:35]
	v_lshlrev_b32_e32 v34, 16, v80
	v_and_b32_e32 v35, 0xffff0000, v80
	v_lshlrev_b32_e32 v38, 16, v81
	v_and_b32_e32 v39, 0xffff0000, v81
	v_pk_add_f32 v[28:29], v[28:29], v[38:39]
	v_pk_add_f32 v[26:27], v[26:27], v[34:35]
	s_mov_b64 s[2:3], -1
	s_and_b64 vcc, exec, s[6:7]
	v_lshlrev_b32_e32 v34, 1, v36
	s_cbranch_vccz .LBB0_429
	v_cvt_pk_bf16_f32 v38, v30, v31
	v_cvt_pk_bf16_f32 v39, v32, v33
	v_cvt_pk_bf16_f32 v40, v26, v27
	v_cvt_pk_bf16_f32 v41, v28, v29
	s_mov_b64 s[2:3], 0
	buffer_store_dwordx4 v[38:41], v34, s[80:83], 0 offen sc1
	s_nop 1
	v_pk_mul_f32 v[38:39], v[32:33], v[32:33]
	v_pk_mul_f32 v[40:41], v[30:31], v[30:31]
	s_nop 0
	v_pk_mov_b32 v[44:45], v[40:41], v[38:39] op_sel:[1,0]
	v_mov_b32_e32 v41, v39
	v_pk_add_f32 v[38:39], v[44:45], v[40:41]
	v_pk_mul_f32 v[40:41], v[28:29], v[28:29]
	v_pk_mul_f32 v[44:45], v[26:27], v[26:27]
	v_mov_b32_e32 v46, v40
	v_mov_b32_e32 v47, v44
	v_mov_b32_e32 v44, v41
	v_pk_add_f32 v[40:41], v[46:47], v[44:45]
	v_add_f32_e32 v38, v38, v39
	v_add_f32_e32 v38, v41, v38
	v_add_f32_e32 v38, v40, v38
.LBB0_429:
	s_andn2_b64 vcc, exec, s[2:3]
	v_lshlrev_b32_e32 v36, 2, v36
	s_cbranch_vccnz .LBB0_431
	v_mov_b32_e32 v38, 0
	buffer_store_dwordx4 v[30:33], v36, s[84:87], 0 offen
	buffer_store_dwordx4 v[26:29], v36, s[84:87], 0 offen offset:16
.LBB0_431:
	s_nop 0
	v_lshlrev_b32_e32 v26, 16, v74
	v_and_b32_e32 v27, 0xffff0000, v74
	v_lshlrev_b32_e32 v28, 16, v75
	v_and_b32_e32 v29, 0xffff0000, v75
	v_pk_add_f32 v[24:25], v[24:25], v[28:29]
	v_pk_add_f32 v[22:23], v[22:23], v[26:27]
	v_lshlrev_b32_e32 v26, 16, v76
	v_and_b32_e32 v27, 0xffff0000, v76
	v_lshlrev_b32_e32 v28, 16, v77
	v_and_b32_e32 v29, 0xffff0000, v77
	v_pk_add_f32 v[20:21], v[20:21], v[28:29]
	v_pk_add_f32 v[18:19], v[18:19], v[26:27]
	s_mov_b64 s[2:3], -1
	s_and_b64 vcc, exec, s[6:7]
	s_cbranch_vccz .LBB0_433
	v_cvt_pk_bf16_f32 v26, v22, v23
	v_cvt_pk_bf16_f32 v27, v24, v25
	v_cvt_pk_bf16_f32 v28, v18, v19
	v_cvt_pk_bf16_f32 v29, v20, v21
	v_add_u32_e32 v30, s8, v34
	buffer_store_dwordx4 v[26:29], v30, s[80:83], 0 offen sc1
	s_nop 1
	v_pk_mul_f32 v[26:27], v[24:25], v[24:25]
	v_pk_mul_f32 v[28:29], v[22:23], v[22:23]
	s_mov_b64 s[2:3], 0
	v_pk_mov_b32 v[30:31], v[28:29], v[26:27] op_sel:[1,0]
	v_mov_b32_e32 v29, v27
	v_pk_add_f32 v[26:27], v[30:31], v[28:29]
	v_pk_mul_f32 v[28:29], v[20:21], v[20:21]
	v_pk_mul_f32 v[30:31], v[18:19], v[18:19]
	v_mov_b32_e32 v32, v28
	v_mov_b32_e32 v33, v30
	v_mov_b32_e32 v30, v29
	v_pk_add_f32 v[28:29], v[32:33], v[30:31]
	v_add_f32_e32 v26, v26, v27
	v_add_f32_e32 v26, v29, v26
	v_add_f32_e32 v26, v28, v26
	v_add_f32_e32 v26, v26, v38
.LBB0_433:
	s_andn2_b64 vcc, exec, s[2:3]
	s_cbranch_vccnz .LBB0_435
	v_mov_b32_e32 v26, v38
	buffer_store_dwordx4 v[22:25], v36, s[84:87], 0 offen offset:512
	buffer_store_dwordx4 v[18:21], v36, s[84:87], 0 offen offset:528
.LBB0_435:
	s_nop 1
	v_lshlrev_b64 v[20:21], 11, v[94:95]
	v_lshlrev_b32_e32 v18, 16, v70
	v_and_b32_e32 v19, 0xffff0000, v70
	v_lshlrev_b32_e32 v22, 16, v71
	v_and_b32_e32 v23, 0xffff0000, v71
	v_or_b32_e32 v20, v20, v174
	v_pk_add_f32 v[16:17], v[16:17], v[22:23]
	v_pk_add_f32 v[14:15], v[14:15], v[18:19]
	v_lshlrev_b32_e32 v18, 16, v72
	v_and_b32_e32 v19, 0xffff0000, v72
	v_lshlrev_b32_e32 v22, 16, v73
	v_and_b32_e32 v23, 0xffff0000, v73
	v_pk_add_f32 v[12:13], v[12:13], v[22:23]
	v_pk_add_f32 v[10:11], v[10:11], v[18:19]
	s_mov_b64 s[2:3], -1
	s_and_b64 vcc, exec, s[6:7]
	v_lshlrev_b32_e32 v18, 1, v20
	s_cbranch_vccz .LBB0_437
	v_cvt_pk_bf16_f32 v22, v14, v15
	v_cvt_pk_bf16_f32 v23, v16, v17
	v_cvt_pk_bf16_f32 v24, v10, v11
	v_cvt_pk_bf16_f32 v25, v12, v13
	s_mov_b64 s[2:3], 0
	buffer_store_dwordx4 v[22:25], v18, s[80:83], 0 offen sc1
	s_nop 1
	v_pk_mul_f32 v[22:23], v[16:17], v[16:17]
	v_pk_mul_f32 v[24:25], v[14:15], v[14:15]
	s_nop 0
	v_pk_mov_b32 v[28:29], v[24:25], v[22:23] op_sel:[1,0]
	v_mov_b32_e32 v25, v23
	v_pk_add_f32 v[22:23], v[28:29], v[24:25]
	v_pk_mul_f32 v[24:25], v[12:13], v[12:13]
	v_pk_mul_f32 v[28:29], v[10:11], v[10:11]
	v_mov_b32_e32 v30, v24
	v_mov_b32_e32 v31, v28
	v_mov_b32_e32 v28, v25
	v_pk_add_f32 v[24:25], v[30:31], v[28:29]
	v_add_f32_e32 v22, v22, v23
	v_add_f32_e32 v22, v25, v22
	v_add_f32_e32 v22, v24, v22
.LBB0_437:
	s_andn2_b64 vcc, exec, s[2:3]
	v_lshlrev_b32_e32 v20, 2, v20
	s_cbranch_vccnz .LBB0_439
	v_mov_b32_e32 v22, 0
	buffer_store_dwordx4 v[14:17], v20, s[84:87], 0 offen
	buffer_store_dwordx4 v[10:13], v20, s[84:87], 0 offen offset:16
.LBB0_439:
	s_nop 0
	v_lshlrev_b32_e32 v10, 16, v66
	v_and_b32_e32 v11, 0xffff0000, v66
	v_lshlrev_b32_e32 v12, 16, v67
	v_and_b32_e32 v13, 0xffff0000, v67
	v_pk_add_f32 v[8:9], v[8:9], v[12:13]
	v_pk_add_f32 v[6:7], v[6:7], v[10:11]
	v_lshlrev_b32_e32 v10, 16, v68
	v_and_b32_e32 v11, 0xffff0000, v68
	v_lshlrev_b32_e32 v12, 16, v69
	v_and_b32_e32 v13, 0xffff0000, v69
	v_pk_add_f32 v[4:5], v[4:5], v[12:13]
	v_pk_add_f32 v[2:3], v[2:3], v[10:11]
	s_mov_b64 s[2:3], -1
	s_and_b64 vcc, exec, s[6:7]
	s_cbranch_vccz .LBB0_441
	v_cvt_pk_bf16_f32 v10, v6, v7
	v_cvt_pk_bf16_f32 v11, v8, v9
	v_cvt_pk_bf16_f32 v12, v2, v3
	v_cvt_pk_bf16_f32 v13, v4, v5
	v_add_u32_e32 v14, s8, v18
	buffer_store_dwordx4 v[10:13], v14, s[80:83], 0 offen sc1
	s_nop 1
	v_pk_mul_f32 v[10:11], v[8:9], v[8:9]
	v_pk_mul_f32 v[12:13], v[6:7], v[6:7]
	s_mov_b64 s[2:3], 0
	v_pk_mov_b32 v[14:15], v[12:13], v[10:11] op_sel:[1,0]
	v_mov_b32_e32 v13, v11
	v_pk_add_f32 v[10:11], v[14:15], v[12:13]
	v_pk_mul_f32 v[12:13], v[4:5], v[4:5]
	v_pk_mul_f32 v[14:15], v[2:3], v[2:3]
	v_mov_b32_e32 v16, v12
	v_mov_b32_e32 v17, v14
	v_mov_b32_e32 v14, v13
	v_pk_add_f32 v[12:13], v[16:17], v[14:15]
	v_add_f32_e32 v10, v10, v11
	v_add_f32_e32 v10, v13, v10
	v_add_f32_e32 v10, v12, v10
	v_add_f32_e32 v10, v10, v22
.LBB0_441:
	s_andn2_b64 vcc, exec, s[2:3]
	s_cbranch_vccnz .LBB0_443
	v_mov_b32_e32 v10, v22
	buffer_store_dwordx4 v[6:9], v20, s[84:87], 0 offen offset:512
	buffer_store_dwordx4 v[2:5], v20, s[84:87], 0 offen offset:528
